# P3b: all 16 V-fragment loads of the four value blocks issued before the first MFMA chain
# baseline (speedup 1.0000x reference)
; #define LAS __attribute__((address_space(3)))
; __device__ __forceinline__ float fexp(float x) { return __builtin_amdgcn_exp2f(x * LOG2E); }
; #define LDS_WAIT() asm volatile("s_waitcnt lgkmcnt(0)" ::: "memory")
; __device__ __forceinline__ s16x8 pack8(const float (&x)[8]) { u32x4 p; p.x = pk2(x[0], x[1]); p.y = pk2(x[2], x[3]); p.z = pk2(x[4], x[5]); p.w = pk2(x[6], x[7]); return __builtin_bit_cast(s16x8, p); }
; __device__ __forceinline__ void unpack8(u32x4 v, float (&x)[8]) { x[0] = bflo(v.x); x[1] = bfhi(v.x); x[2] = bflo(v.y); x[3] = bfhi(v.y); x[4] = bflo(v.z); x[5] = bfhi(v.z); x[6] = bflo(v.w); x[7] = bfhi(v.w); }
;     __device__ __forceinline__ bf16* KVt() const { return (bf16*)(ws + WS_KVT); }
;     __device__ __forceinline__ float* GATES() const { return (float*)(ws + WS_GATES); }
; template <bool SAMPLE>
; __device__ __forceinline__ void mstate_task(Ctx& C, int l, int unit, int h, int dblk, LAS float* wbuf) {
;     ...
;     const bool valid = lane < L;
;     const float li = valid ? C.GATES()[(grow0 + lane) * 8 + h] : -1e30f, lf = valid ? C.GATES()[(grow0 + lane) * 8 + 4 + h] : 0.f;
;     const float bc = scan_add(lf, lane), Bc = __shfl(bc, L - 1);
;     const float uu = valid ? Bc - bc + li : -1e30f, Mc = wave_max(uu);
;     const float w = valid ? fexp(uu - Mc) : 0.f;
;     wbuf[lane] = w;
;     LDS_WAIT();
;     const int d = 32 * dblk + r;
;     const bf16* krow = C.KVt() + (size_t)(R_KM + h * 128 + d) * MT + grow0;
;     float dn = 0.f; s16x8 Bf[NKS];
;     { u32x4 kq[NKS];
; #pragma unroll
;       for (int ks = 0; ks < NKS; ++ks) kq[ks] = *(const u32x4*)(krow + 16 * ks + 8 * hi);
; #pragma unroll
;       for (int ks = 0; ks < NKS; ++ks) { const int s0 = 16 * ks + 8 * hi;
;         float kc[8]; unpack8(kq[ks], kc);
;         const f32x4 w0 = *(const LAS f32x4*)(wbuf + s0), w1 = *(const LAS f32x4*)(wbuf + s0 + 4);
; #pragma unroll
;         for (int e = 0; e < 8; ++e) { kc[e] *= (e < 4 ? w0[e] : w1[e - 4]); dn += kc[e]; }
;         Bf[ks] = pack8(kc); } }
.LBB0_622:
	s_mov_b64 s[2:3], -1
	v_and_b32_e32 v40, 63, v202
	v_lshrrev_b32_e32 v41, 5, v40
	v_and_b32_e32 v0, 32, v202
	v_readfirstlane_b32 s23, v202
	s_cmp_gt_i32 s72, 63
	v_and_b32_e32 v42, 31, v202
	v_cmp_eq_u32_e64 s[12:13], 0, v40
	v_cmp_gt_u32_e64 s[10:11], 2, v40
	v_cmp_gt_u32_e64 s[8:9], 4, v40
	v_cmp_gt_u32_e64 s[6:7], 8, v40
	v_cmp_gt_u32_e64 s[4:5], 16, v40
	v_cmp_gt_u32_e32 vcc, 32, v40
	v_lshl_add_u32 v44, v40, 2, s22
	v_lshlrev_b32_e32 v192, 4, v41
	v_add_u32_e32 v43, s22, v0
	s_cbranch_scc0 .LBB0_628
	s_sub_i32 s2, s72, 64
	s_lshr_b32 s19, s2, 1
	s_lshl_b32 s2, s72, 1
	s_and_b32 s2, s2, 2
	s_ashr_i32 s3, s23, 8
	s_add_i32 s20, s3, s2
	s_lshl_b32 s2, s19, 2
	s_add_i32 s18, s20, s2
	v_lshl_or_b32 v0, s19, 6, v40
	s_waitcnt lgkmcnt(0)
	v_mov_b32_e32 v1, v193
	v_readlane_b32 s2, v254, 55
	s_ashr_i32 s21, s20, 31
	v_lshlrev_b64 v[0:1], 5, v[0:1]
	v_readlane_b32 s3, v254, 56
	s_bfe_u32 s34, s23, 0x20006
	v_lshl_or_b32 v47, s34, 5, v42
	v_lshl_add_u64 v[2:3], s[2:3], 0, v[0:1]
	s_lshl_b64 s[2:3], s[20:21], 2
	v_lshl_add_u64 v[0:1], s[90:91], 0, v[0:1]
	v_lshl_add_u64 v[2:3], v[2:3], 0, s[2:3]
	v_lshl_add_u64 v[0:1], v[0:1], 0, s[2:3]
	s_mov_b32 s2, 0x1f518000
	v_add_co_u32_e64 v0, s[2:3], s2, v0
	global_load_dword v2, v[2:3], off
	s_nop 0
	v_addc_co_u32_e64 v1, s[2:3], 0, v1, s[2:3]
	global_load_dword v0, v[0:1], off offset:16
	v_and_b32_e32 v1, 64, v220
	v_add_u32_e32 v3, -1, v220
	v_cmp_lt_i32_e64 s[2:3], v3, v1
	s_lshl_b32 s78, s19, 7
	s_ashr_i32 s19, s18, 31
	v_cndmask_b32_e64 v3, v3, v220, s[2:3]
	v_lshlrev_b32_e32 v3, 2, v3
	v_lshlrev_b32_e32 v34, 1, v47
	v_lshl_or_b32 v38, v41, 10, v34
	v_mov_b32_e32 v39, v193
	s_waitcnt vmcnt(0)
	ds_bpermute_b32 v3, v3, v0
	s_waitcnt lgkmcnt(0)
	v_add_f32_e32 v3, v0, v3
	v_cndmask_b32_e64 v0, v3, v0, s[12:13]
	v_add_u32_e32 v3, -2, v220
	v_cmp_lt_i32_e64 s[2:3], v3, v1
	s_nop 1
	v_cndmask_b32_e64 v3, v3, v220, s[2:3]
	v_lshlrev_b32_e32 v3, 2, v3
	ds_bpermute_b32 v3, v3, v0
	s_waitcnt lgkmcnt(0)
	v_add_f32_e32 v3, v0, v3
	v_cndmask_b32_e64 v0, v3, v0, s[10:11]
	v_add_u32_e32 v3, -4, v220
	v_cmp_lt_i32_e64 s[2:3], v3, v1
	s_nop 1
	v_cndmask_b32_e64 v3, v3, v220, s[2:3]
	v_lshlrev_b32_e32 v3, 2, v3
	ds_bpermute_b32 v3, v3, v0
	s_waitcnt lgkmcnt(0)
	v_add_f32_e32 v3, v0, v3
	v_cndmask_b32_e64 v0, v3, v0, s[8:9]
	v_add_u32_e32 v3, -8, v220
	v_cmp_lt_i32_e64 s[2:3], v3, v1
	s_nop 1
	v_cndmask_b32_e64 v3, v3, v220, s[2:3]
	v_lshlrev_b32_e32 v3, 2, v3
	ds_bpermute_b32 v3, v3, v0
	s_waitcnt lgkmcnt(0)
	v_add_f32_e32 v3, v0, v3
	v_cndmask_b32_e64 v0, v3, v0, s[6:7]
	v_add_u32_e32 v3, -16, v220
	v_cmp_lt_i32_e64 s[2:3], v3, v1
	v_readlane_b32 s6, v254, 53
	v_readlane_b32 s7, v254, 54
	v_cndmask_b32_e64 v3, v3, v220, s[2:3]
	v_lshlrev_b32_e32 v3, 2, v3
	ds_bpermute_b32 v3, v3, v0
	s_waitcnt lgkmcnt(0)
	v_add_f32_e32 v3, v0, v3
	v_cndmask_b32_e64 v0, v3, v0, s[4:5]
	v_subrev_u32_e32 v3, 32, v220
	v_cmp_lt_i32_e64 s[2:3], v3, v1
	v_add_u32_e32 v1, 64, v1
	s_nop 0
	v_cndmask_b32_e64 v3, v3, v220, s[2:3]
	v_lshlrev_b32_e32 v3, 2, v3
	ds_bpermute_b32 v3, v3, v0
	s_waitcnt lgkmcnt(0)
	v_add_f32_e32 v3, v0, v3
	v_cndmask_b32_e32 v0, v3, v0, vcc
	v_bfrev_b32_e32 v3, 0.5
	v_lshl_or_b32 v3, v220, 2, v3
	ds_bpermute_b32 v45, v3, v0
	v_xor_b32_e32 v3, 2, v220
	s_waitcnt lgkmcnt(0)
	v_sub_f32_e32 v0, v45, v0
	v_add_f32_e32 v0, v2, v0
	v_xor_b32_e32 v2, 1, v220
	v_cmp_lt_i32_e64 s[2:3], v2, v1
	s_nop 1
	v_cndmask_b32_e64 v2, v220, v2, s[2:3]
	v_lshlrev_b32_e32 v2, 2, v2
	ds_bpermute_b32 v2, v2, v0
	v_cmp_lt_i32_e64 s[2:3], v3, v1
	s_waitcnt lgkmcnt(0)
	v_max_f32_e32 v2, v2, v2
	v_cndmask_b32_e64 v3, v220, v3, s[2:3]
	v_max_f32_e32 v2, v0, v2
	v_lshlrev_b32_e32 v3, 2, v3
	ds_bpermute_b32 v3, v3, v2
	s_waitcnt lgkmcnt(0)
	v_max_f32_e32 v3, v3, v3
	v_max_f32_e32 v2, v2, v3
	v_xor_b32_e32 v3, 4, v220
	v_cmp_lt_i32_e64 s[2:3], v3, v1
	s_nop 1
	v_cndmask_b32_e64 v3, v220, v3, s[2:3]
	v_lshlrev_b32_e32 v3, 2, v3
	ds_bpermute_b32 v3, v3, v2
	s_waitcnt lgkmcnt(0)
	v_max_f32_e32 v3, v3, v3
	v_max_f32_e32 v2, v2, v3
	v_xor_b32_e32 v3, 8, v220
	v_cmp_lt_i32_e64 s[2:3], v3, v1
	s_nop 1
	v_cndmask_b32_e64 v3, v220, v3, s[2:3]
	v_lshlrev_b32_e32 v3, 2, v3
	ds_bpermute_b32 v3, v3, v2
	s_waitcnt lgkmcnt(0)
	v_max_f32_e32 v3, v3, v3
	v_max_f32_e32 v2, v2, v3
	v_xor_b32_e32 v3, 16, v220
	v_cmp_lt_i32_e64 s[2:3], v3, v1
	s_nop 1
	v_cndmask_b32_e64 v3, v220, v3, s[2:3]
	v_lshlrev_b32_e32 v3, 2, v3
	ds_bpermute_b32 v3, v3, v2
	s_waitcnt lgkmcnt(0)
	v_max_f32_e32 v3, v3, v3
	v_max_f32_e32 v2, v2, v3
	v_xor_b32_e32 v3, 32, v220
	v_cmp_lt_i32_e64 s[2:3], v3, v1
	s_nop 1
	v_cndmask_b32_e64 v1, v220, v3, s[2:3]
	v_lshlrev_b32_e32 v48, 2, v1
	ds_bpermute_b32 v1, v48, v2
	s_lshl_b32 s2, s20, 7
	s_add_i32 s3, s2, 0x400
	s_waitcnt lgkmcnt(0)
	v_max_f32_e32 v1, v1, v1
	v_max_f32_e32 v46, v2, v1
	v_sub_f32_e32 v0, v0, v46
	v_mul_f32_e32 v0, 0x3fb8aa3b, v0
	v_exp_f32_e32 v0, v0
	v_or_b32_e32 v2, s3, v47
	ds_write_b32 v44, v0 offset:16384
	v_mov_b64_e32 v[0:1], s[74:75]
	v_mad_i64_i32 v[0:1], s[4:5], v2, s81, v[0:1]
	v_lshl_add_u64 v[0:1], v[0:1], 0, s[78:79]
	s_waitcnt lgkmcnt(0)
	v_lshl_add_u64 v[12:13], v[0:1], 0, v[192:193]
	global_load_dwordx4 v[0:3], v[12:13], off
	global_load_dwordx4 v[4:7], v[12:13], off offset:32
	global_load_dwordx4 v[8:11], v[12:13], off offset:64
	s_nop 0
	global_load_dwordx4 v[12:15], v[12:13], off offset:96
	ds_read_b128 v[16:19], v43 offset:16384
	ds_read_b128 v[20:23], v43 offset:16400
	s_lshl_b64 s[4:5], s[18:19], 15
	s_add_u32 s4, s6, s4
	s_addc_u32 s5, s7, s5
	s_addk_i32 s2, 0x200
	v_lshl_add_u64 v[34:35], s[4:5], 0, v[38:39]
	s_waitcnt vmcnt(3)
	v_lshlrev_b32_e32 v24, 16, v0
	v_and_b32_e32 v25, 0xffff0000, v0
	s_waitcnt lgkmcnt(1)
; #define LAS __attribute__((address_space(3)))
; #define MFMA32(a, b, c) __builtin_amdgcn_mfma_f32_32x32x16_bf16((a), (b), (c), 0, 0, 0)
; __device__ __forceinline__ s16x8 pack8(const float (&x)[8]) { u32x4 p; p.x = pk2(x[0], x[1]); p.y = pk2(x[2], x[3]); p.z = pk2(x[4], x[5]); p.w = pk2(x[6], x[7]); return __builtin_bit_cast(s16x8, p); }
; __device__ __forceinline__ void unpack8(u32x4 v, float (&x)[8]) { x[0] = bflo(v.x); x[1] = bfhi(v.x); x[2] = bflo(v.y); x[3] = bfhi(v.y); x[4] = bflo(v.z); x[5] = bfhi(v.z); x[6] = bflo(v.w); x[7] = bfhi(v.w); }
;     __device__ __forceinline__ bf16* KVt() const { return (bf16*)(ws + WS_KVT); }
;     __device__ __forceinline__ bf16* DC() const { return (bf16*)(ws + WS_XN); }
;     __device__ __forceinline__ bf16* DCS() const { return (bf16*)(ws + WS_DCS); }
; template <bool SAMPLE>
; __device__ __forceinline__ void mstate_task(Ctx& C, int l, int unit, int h, int dblk, LAS float* wbuf) {
;     ...
;       for (int ks = 0; ks < NKS; ++ks) { const int s0 = 16 * ks + 8 * hi;
;         float kc[8]; unpack8(kq[ks], kc);
;         const f32x4 w0 = *(const LAS f32x4*)(wbuf + s0), w1 = *(const LAS f32x4*)(wbuf + s0 + 4);
; #pragma unroll
;         for (int e = 0; e < 8; ++e) { kc[e] *= (e < 4 ? w0[e] : w1[e - 4]); dn += kc[e]; }
;         Bf[ks] = pack8(kc); } }
;     bf16* dcp = (SAMPLE ? C.DCS() + (size_t)(slot - NSLOT_P) * 16384 : C.DC() + (size_t)slot * 16384);
; #pragma unroll
;     for (int vb = 0; vb < 4; ++vb) {
;         f32x16 acc;
; #pragma unroll
;         for (int i = 0; i < 16; ++i) acc[i] = 0.f;
;         const bf16* vrow = C.KVt() + (size_t)(R_VM + h * 128 + 32 * vb + r) * MT + grow0 + 8 * hi;
;         s16x8 af[NKS];
; #pragma unroll
;         for (int ks = 0; ks < NKS; ++ks) af[ks] = *(const s16x8*)(vrow + 16 * ks);
; #pragma unroll
;         for (int ks = 0; ks < NKS; ++ks) acc = MFMA32(af[ks], Bf[ks], acc);
	v_pk_mul_f32 v[16:17], v[16:17], v[24:25]
	s_waitcnt vmcnt(2)
	v_and_b32_e32 v25, 0xffff0000, v4
	v_add_f32_e32 v0, 0, v16
	v_add_f32_e32 v24, v17, v0
	v_lshlrev_b32_e32 v0, 16, v1
	v_and_b32_e32 v1, 0xffff0000, v1
	v_pk_mul_f32 v[0:1], v[18:19], v[0:1]
	v_and_b32_e32 v19, 0xffff0000, v2
	v_add_f32_e32 v18, v0, v24
	v_add_f32_e32 v24, v1, v18
	v_lshlrev_b32_e32 v18, 16, v2
	s_waitcnt lgkmcnt(0)
	v_pk_mul_f32 v[18:19], v[20:21], v[18:19]
	v_cvt_pk_bf16_f32 v16, v16, v17
	v_add_f32_e32 v2, v18, v24
	v_add_f32_e32 v20, v19, v2
	v_lshlrev_b32_e32 v2, 16, v3
	v_and_b32_e32 v3, 0xffff0000, v3
	v_pk_mul_f32 v[2:3], v[22:23], v[2:3]
	v_cvt_pk_bf16_f32 v17, v0, v1
	v_add_f32_e32 v20, v2, v20
	v_add_f32_e32 v26, v3, v20
	v_cvt_pk_bf16_f32 v18, v18, v19
	v_cvt_pk_bf16_f32 v19, v2, v3
	ds_read_b128 v[0:3], v43 offset:16448
	ds_read_b128 v[20:23], v43 offset:16464
	v_lshlrev_b32_e32 v24, 16, v4
	s_waitcnt lgkmcnt(1)
	v_pk_mul_f32 v[0:1], v[0:1], v[24:25]
	s_nop 0
	v_add_f32_e32 v4, v0, v26
	v_add_f32_e32 v24, v1, v4
	v_lshlrev_b32_e32 v4, 16, v5
	v_and_b32_e32 v5, 0xffff0000, v5
	v_pk_mul_f32 v[2:3], v[2:3], v[4:5]
	v_and_b32_e32 v5, 0xffff0000, v6
	v_add_f32_e32 v4, v2, v24
	v_add_f32_e32 v24, v3, v4
	v_lshlrev_b32_e32 v4, 16, v6
	s_waitcnt lgkmcnt(0)
	v_pk_mul_f32 v[4:5], v[20:21], v[4:5]
	v_cvt_pk_bf16_f32 v21, v2, v3
	v_add_f32_e32 v6, v4, v24
	v_add_f32_e32 v20, v5, v6
	v_lshlrev_b32_e32 v6, 16, v7
	v_and_b32_e32 v7, 0xffff0000, v7
	v_pk_mul_f32 v[6:7], v[22:23], v[6:7]
	v_cvt_pk_bf16_f32 v22, v4, v5
	v_add_f32_e32 v20, v6, v20
	v_add_f32_e32 v26, v7, v20
	v_cvt_pk_bf16_f32 v20, v0, v1
	v_cvt_pk_bf16_f32 v23, v6, v7
	ds_read_b128 v[0:3], v43 offset:16512
	ds_read_b128 v[4:7], v43 offset:16528
	s_waitcnt vmcnt(1)
	v_lshlrev_b32_e32 v24, 16, v8
	v_and_b32_e32 v25, 0xffff0000, v8
	s_waitcnt lgkmcnt(1)
	v_pk_mul_f32 v[0:1], v[0:1], v[24:25]
	s_nop 0
	v_add_f32_e32 v8, v0, v26
	v_add_f32_e32 v24, v1, v8
	v_lshlrev_b32_e32 v8, 16, v9
	v_and_b32_e32 v9, 0xffff0000, v9
	v_pk_mul_f32 v[2:3], v[2:3], v[8:9]
	v_and_b32_e32 v9, 0xffff0000, v10
	v_add_f32_e32 v8, v2, v24
	v_add_f32_e32 v24, v3, v8
	v_lshlrev_b32_e32 v8, 16, v10
	s_waitcnt lgkmcnt(0)
	v_pk_mul_f32 v[4:5], v[4:5], v[8:9]
	v_and_b32_e32 v9, 0xffff0000, v11
	v_add_f32_e32 v8, v4, v24
	v_add_f32_e32 v10, v5, v8
	v_lshlrev_b32_e32 v8, 16, v11
	v_pk_mul_f32 v[6:7], v[6:7], v[8:9]
	v_cvt_pk_bf16_f32 v24, v0, v1
	v_add_f32_e32 v8, v6, v10
	v_add_f32_e32 v10, v7, v8
	v_cvt_pk_bf16_f32 v25, v2, v3
	v_cvt_pk_bf16_f32 v26, v4, v5
	v_cvt_pk_bf16_f32 v27, v6, v7
	ds_read_b128 v[0:3], v43 offset:16576
	ds_read_b128 v[4:7], v43 offset:16592
	s_waitcnt vmcnt(0)
	v_lshlrev_b32_e32 v8, 16, v12
	v_and_b32_e32 v9, 0xffff0000, v12
	s_waitcnt lgkmcnt(1)
	v_pk_mul_f32 v[0:1], v[0:1], v[8:9]
	s_nop 0
	v_add_f32_e32 v8, v0, v10
	v_add_f32_e32 v10, v1, v8
	v_lshlrev_b32_e32 v8, 16, v13
	v_and_b32_e32 v9, 0xffff0000, v13
	v_pk_mul_f32 v[2:3], v[2:3], v[8:9]
	v_and_b32_e32 v9, 0xffff0000, v14
	v_add_f32_e32 v8, v2, v10
	v_add_f32_e32 v10, v3, v8
	v_lshlrev_b32_e32 v8, 16, v14
	s_waitcnt lgkmcnt(0)
	v_pk_mul_f32 v[4:5], v[4:5], v[8:9]
	v_and_b32_e32 v9, 0xffff0000, v15
	v_add_f32_e32 v8, v4, v10
	v_add_f32_e32 v10, v5, v8
	v_lshlrev_b32_e32 v8, 16, v15
	v_pk_mul_f32 v[32:33], v[6:7], v[8:9]
	v_cvt_pk_bf16_f32 v30, v4, v5
	v_add_f32_e32 v49, v32, v10
	v_cvt_pk_bf16_f32 v31, v32, v33
	v_or_b32_e32 v32, s2, v42
	s_add_u32 s2, s74, s78
	s_addc_u32 s3, s75, 0
	v_lshl_add_u64 v[36:37], s[2:3], 0, v[192:193]
	v_mad_i64_i32 v[4:5], s[2:3], v32, s81, v[36:37]
	v_cvt_pk_bf16_f32 v28, v0, v1
	v_cvt_pk_bf16_f32 v29, v2, v3
	v_mad_i64_i32 v[62:63], s[2:3], v32, s81, v[36:37]
	v_or_b32_e32 v78, 32, v32
	v_mad_i64_i32 v[64:65], s[2:3], v78, s81, v[36:37]
	v_or_b32_e32 v78, 64, v32
	v_mad_i64_i32 v[66:67], s[2:3], v78, s81, v[36:37]
	v_or_b32_e32 v78, 0x60, v32
	v_mad_i64_i32 v[68:69], s[2:3], v78, s81, v[36:37]
	global_load_dwordx4 v[126:129], v[62:63], off
	global_load_dwordx4 v[130:133], v[62:63], off offset:32
	global_load_dwordx4 v[134:137], v[62:63], off offset:64
	global_load_dwordx4 v[138:141], v[62:63], off offset:96
	global_load_dwordx4 v[142:145], v[64:65], off
	global_load_dwordx4 v[146:149], v[64:65], off offset:32
	global_load_dwordx4 v[150:153], v[64:65], off offset:64
	global_load_dwordx4 v[154:157], v[64:65], off offset:96
	global_load_dwordx4 v[158:161], v[66:67], off
	global_load_dwordx4 v[162:165], v[66:67], off offset:32
	global_load_dwordx4 v[166:169], v[66:67], off offset:64
	global_load_dwordx4 v[170:173], v[66:67], off offset:96
	global_load_dwordx4 v[174:177], v[68:69], off
	global_load_dwordx4 v[178:181], v[68:69], off offset:32
	global_load_dwordx4 v[70:73], v[68:69], off offset:64
	global_load_dwordx4 v[74:77], v[68:69], off offset:96
	s_waitcnt vmcnt(15)
	v_mfma_f32_32x32x16_bf16 v[0:15], v[126:129], v[16:19], 0
	s_waitcnt vmcnt(14)
	v_mfma_f32_32x32x16_bf16 v[0:15], v[130:133], v[20:23], v[0:15]
	s_waitcnt vmcnt(13)
	v_mfma_f32_32x32x16_bf16 v[0:15], v[134:137], v[24:27], v[0:15]
	s_waitcnt vmcnt(12)
; __device__ __forceinline__ bf16 f2bf(float f) { return (bf16)(pk2(f, 0.f) & 0xffffu); }
; #define MFMA32(a, b, c) __builtin_amdgcn_mfma_f32_32x32x16_bf16((a), (b), (c), 0, 0, 0)
;     __device__ __forceinline__ bf16* KVt() const { return (bf16*)(ws + WS_KVT); }
; template <bool SAMPLE>
; __device__ __forceinline__ void mstate_task(Ctx& C, int l, int unit, int h, int dblk, LAS float* wbuf) {
;     ...
;         const bf16* vrow = C.KVt() + (size_t)(R_VM + h * 128 + 32 * vb + r) * MT + grow0 + 8 * hi;
;         s16x8 af[NKS];
; #pragma unroll
;         for (int ks = 0; ks < NKS; ++ks) af[ks] = *(const s16x8*)(vrow + 16 * ks);
; #pragma unroll
;         for (int ks = 0; ks < NKS; ++ks) acc = MFMA32(af[ks], Bf[ks], acc);
; #pragma unroll
;         for (int i = 0; i < 16; ++i) { const int v = 32 * vb + 8 * (i >> 2) + 4 * hi + (i & 3); dcp[v * 128 + d] = f2bf(acc[i]); }
	v_mfma_f32_32x32x16_bf16 v[0:15], v[138:141], v[28:31], v[0:15]
	s_nop 11
	v_cvt_pk_bf16_f32 v0, v0, s0
	global_store_short v38, v0, s[4:5]
	v_cvt_pk_bf16_f32 v0, v1, s0
	global_store_short v38, v0, s[4:5] offset:256
	v_cvt_pk_bf16_f32 v0, v2, s0
	global_store_short v38, v0, s[4:5] offset:512
	v_cvt_pk_bf16_f32 v0, v3, s0
	global_store_short v38, v0, s[4:5] offset:768
	v_cvt_pk_bf16_f32 v0, v4, s0
	global_store_short v38, v0, s[4:5] offset:2048
	v_cvt_pk_bf16_f32 v0, v5, s0
	global_store_short v38, v0, s[4:5] offset:2304
	v_cvt_pk_bf16_f32 v0, v6, s0
	global_store_short v38, v0, s[4:5] offset:2560
	v_cvt_pk_bf16_f32 v0, v7, s0
	global_store_short v38, v0, s[4:5] offset:2816
	v_add_co_u32_e64 v0, s[2:3], s60, v34
	v_cvt_pk_bf16_f32 v2, v8, s0
	s_nop 0
	v_addc_co_u32_e64 v1, s[2:3], 0, v35, s[2:3]
	v_add_co_u32_e64 v38, s[2:3], s36, v34
	s_nop 1
	v_addc_co_u32_e64 v39, s[2:3], 0, v35, s[2:3]
	global_store_short v[38:39], v2, off offset:-4096
	v_cvt_pk_bf16_f32 v2, v9, s0
	global_store_short v[0:1], v2, off offset:256
	v_cvt_pk_bf16_f32 v2, v10, s0
	global_store_short v[0:1], v2, off offset:512
	v_cvt_pk_bf16_f32 v2, v11, s0
	global_store_short v[0:1], v2, off offset:768
	v_cvt_pk_bf16_f32 v2, v12, s0
	global_store_short v[0:1], v2, off offset:2048
	v_cvt_pk_bf16_f32 v2, v13, s0
	global_store_short v[0:1], v2, off offset:2304
	v_cvt_pk_bf16_f32 v2, v14, s0
	global_store_short v[0:1], v2, off offset:2560
	v_cvt_pk_bf16_f32 v2, v15, s0
	global_store_short v[0:1], v2, off offset:2816
	v_or_b32_e32 v0, 32, v32
	v_mad_i64_i32 v[0:1], s[2:3], v0, s81, v[36:37]
	s_waitcnt vmcnt(27)
	v_mfma_f32_32x32x16_bf16 v[0:15], v[142:145], v[16:19], 0
	s_waitcnt vmcnt(26)
	v_mfma_f32_32x32x16_bf16 v[0:15], v[146:149], v[20:23], v[0:15]
	s_waitcnt vmcnt(25)
	v_mfma_f32_32x32x16_bf16 v[0:15], v[150:153], v[24:27], v[0:15]
	s_waitcnt vmcnt(24)
	v_mfma_f32_32x32x16_bf16 v[0:15], v[154:157], v[28:31], v[0:15]
	s_nop 11
	v_cvt_pk_bf16_f32 v0, v0, s0
	global_store_short v[38:39], v0, off
	v_cvt_pk_bf16_f32 v0, v1, s0
	global_store_short v[38:39], v0, off offset:256
	v_cvt_pk_bf16_f32 v0, v2, s0
	global_store_short v[38:39], v0, off offset:512
	v_cvt_pk_bf16_f32 v0, v3, s0
	global_store_short v[38:39], v0, off offset:768
	v_cvt_pk_bf16_f32 v0, v4, s0
	global_store_short v[38:39], v0, off offset:2048
	v_cvt_pk_bf16_f32 v0, v5, s0
	global_store_short v[38:39], v0, off offset:2304
	v_cvt_pk_bf16_f32 v0, v6, s0
	global_store_short v[38:39], v0, off offset:2560
	v_cvt_pk_bf16_f32 v0, v7, s0
	global_store_short v[38:39], v0, off offset:2816
	v_add_co_u32_e64 v0, s[2:3], s38, v34
	v_cvt_pk_bf16_f32 v2, v8, s0
	s_nop 0
	v_addc_co_u32_e64 v1, s[2:3], 0, v35, s[2:3]
	s_movk_i32 s2, 0x4000
	s_nop 0
	v_add_co_u32_e64 v38, s[2:3], s2, v34
	s_nop 1
	v_addc_co_u32_e64 v39, s[2:3], 0, v35, s[2:3]
	global_store_short v[38:39], v2, off offset:-4096
	v_cvt_pk_bf16_f32 v2, v9, s0
	global_store_short v[0:1], v2, off offset:256
	v_cvt_pk_bf16_f32 v2, v10, s0
	global_store_short v[0:1], v2, off offset:512
	v_cvt_pk_bf16_f32 v2, v11, s0
	global_store_short v[0:1], v2, off offset:768
	v_cvt_pk_bf16_f32 v2, v12, s0
	global_store_short v[0:1], v2, off offset:2048
	v_cvt_pk_bf16_f32 v2, v13, s0
	global_store_short v[0:1], v2, off offset:2304
	v_cvt_pk_bf16_f32 v2, v14, s0
	global_store_short v[0:1], v2, off offset:2560
	v_cvt_pk_bf16_f32 v2, v15, s0
	global_store_short v[0:1], v2, off offset:2816
	v_or_b32_e32 v0, 64, v32
	v_mad_i64_i32 v[4:5], s[2:3], v0, s81, v[36:37]
	s_waitcnt vmcnt(39)
	v_mfma_f32_32x32x16_bf16 v[0:15], v[158:161], v[16:19], 0
	s_waitcnt vmcnt(38)
	v_mfma_f32_32x32x16_bf16 v[0:15], v[162:165], v[20:23], v[0:15]
	s_waitcnt vmcnt(37)
; __device__ __forceinline__ bf16 f2bf(float f) { return (bf16)(pk2(f, 0.f) & 0xffffu); }
; #define LDS_WAIT() asm volatile("s_waitcnt lgkmcnt(0)" ::: "memory")
; #define MFMA32(a, b, c) __builtin_amdgcn_mfma_f32_32x32x16_bf16((a), (b), (c), 0, 0, 0)
;     __device__ __forceinline__ bf16* KVt() const { return (bf16*)(ws + WS_KVT); }
;     __device__ __forceinline__ float* DN() const { return (float*)(ws + WS_DN); }
;     __device__ __forceinline__ float* MBM() const { return (float*)(ws + WS_MB); }
;     __device__ __forceinline__ float* MBB() const { return (float*)(ws + WS_MB) + (NSLOT_P + NSLOT_S); }
; template <bool SAMPLE>
; __device__ __forceinline__ void mstate_task(Ctx& C, int l, int unit, int h, int dblk, LAS float* wbuf) {
;     ...
;         const bf16* vrow = C.KVt() + (size_t)(R_VM + h * 128 + 32 * vb + r) * MT + grow0 + 8 * hi;
;         s16x8 af[NKS];
; #pragma unroll
;         for (int ks = 0; ks < NKS; ++ks) af[ks] = *(const s16x8*)(vrow + 16 * ks);
; #pragma unroll
;         for (int ks = 0; ks < NKS; ++ks) acc = MFMA32(af[ks], Bf[ks], acc);
; #pragma unroll
;         for (int i = 0; i < 16; ++i) { const int v = 32 * vb + 8 * (i >> 2) + 4 * hi + (i & 3); dcp[v * 128 + d] = f2bf(acc[i]); }
;     }
;     dn += __shfl_xor(dn, 32);
;     if (hi == 0) C.DN()[(size_t)slot * 128 + d] = dn;
;     if (dblk == 0 && lane == 0) { C.MBM()[slot] = Mc; C.MBB()[slot] = Bc; }
;     LDS_WAIT();
	v_mfma_f32_32x32x16_bf16 v[0:15], v[166:169], v[24:27], v[0:15]
	s_waitcnt vmcnt(36)
	v_mfma_f32_32x32x16_bf16 v[0:15], v[170:173], v[28:31], v[0:15]
	s_nop 11
	v_cvt_pk_bf16_f32 v0, v0, s0
	global_store_short v[38:39], v0, off
	v_cvt_pk_bf16_f32 v0, v1, s0
	global_store_short v[38:39], v0, off offset:256
	v_cvt_pk_bf16_f32 v0, v2, s0
	global_store_short v[38:39], v0, off offset:512
	v_cvt_pk_bf16_f32 v0, v3, s0
	global_store_short v[38:39], v0, off offset:768
	v_cvt_pk_bf16_f32 v0, v4, s0
	global_store_short v[38:39], v0, off offset:2048
	v_cvt_pk_bf16_f32 v0, v5, s0
	global_store_short v[38:39], v0, off offset:2304
	v_cvt_pk_bf16_f32 v0, v6, s0
	global_store_short v[38:39], v0, off offset:2560
	v_cvt_pk_bf16_f32 v0, v7, s0
	global_store_short v[38:39], v0, off offset:2816
	v_add_co_u32_e64 v0, s[2:3], s35, v34
	v_cvt_pk_bf16_f32 v2, v8, s0
	s_nop 0
	v_addc_co_u32_e64 v1, s[2:3], 0, v35, s[2:3]
	v_add_co_u32_e64 v58, s[2:3], s93, v34
	s_nop 1
	v_addc_co_u32_e64 v59, s[2:3], 0, v35, s[2:3]
	global_store_short v[58:59], v2, off offset:-4096
	v_cvt_pk_bf16_f32 v2, v9, s0
	global_store_short v[0:1], v2, off offset:256
	v_cvt_pk_bf16_f32 v2, v10, s0
	global_store_short v[0:1], v2, off offset:512
	v_cvt_pk_bf16_f32 v2, v11, s0
	global_store_short v[0:1], v2, off offset:768
	v_cvt_pk_bf16_f32 v2, v12, s0
	global_store_short v[0:1], v2, off offset:2048
	v_cvt_pk_bf16_f32 v2, v13, s0
	global_store_short v[0:1], v2, off offset:2304
	v_cvt_pk_bf16_f32 v2, v14, s0
	global_store_short v[0:1], v2, off offset:2560
	v_cvt_pk_bf16_f32 v2, v15, s0
	global_store_short v[0:1], v2, off offset:2816
	v_or_b32_e32 v0, 0x60, v32
	v_mad_i64_i32 v[4:5], s[2:3], v0, s81, v[36:37]
	s_waitcnt vmcnt(51)
	v_mfma_f32_32x32x16_bf16 v[0:15], v[174:177], v[16:19], 0
	s_movk_i32 s2, 0x7000
	s_waitcnt vmcnt(50)
	v_mfma_f32_32x32x16_bf16 v[0:15], v[178:181], v[20:23], v[0:15]
	s_waitcnt vmcnt(49)
	v_mfma_f32_32x32x16_bf16 v[0:15], v[70:73], v[24:27], v[0:15]
	s_waitcnt vmcnt(48)
	v_mfma_f32_32x32x16_bf16 v[0:15], v[74:77], v[28:31], v[0:15]
	s_nop 11
	v_cvt_pk_bf16_f32 v0, v0, s0
	global_store_short v[58:59], v0, off
	v_cvt_pk_bf16_f32 v0, v1, s0
	global_store_short v[58:59], v0, off offset:256
	v_cvt_pk_bf16_f32 v0, v2, s0
	global_store_short v[58:59], v0, off offset:512
	v_cvt_pk_bf16_f32 v0, v3, s0
	global_store_short v[58:59], v0, off offset:768
	v_cvt_pk_bf16_f32 v0, v4, s0
	global_store_short v[58:59], v0, off offset:2048
	v_cvt_pk_bf16_f32 v0, v5, s0
	global_store_short v[58:59], v0, off offset:2304
	v_cvt_pk_bf16_f32 v0, v6, s0
	global_store_short v[58:59], v0, off offset:2560
	v_cvt_pk_bf16_f32 v0, v7, s0
	global_store_short v[58:59], v0, off offset:2816
	v_add_co_u32_e64 v0, s[2:3], s2, v34
	v_cvt_pk_bf16_f32 v2, v8, s0
	s_nop 0
	v_addc_co_u32_e64 v1, s[2:3], 0, v35, s[2:3]
	global_store_short v[0:1], v2, off
	v_cvt_pk_bf16_f32 v2, v9, s0
	global_store_short v[0:1], v2, off offset:256
	v_cvt_pk_bf16_f32 v2, v10, s0
	global_store_short v[0:1], v2, off offset:512
	v_cvt_pk_bf16_f32 v2, v11, s0
	global_store_short v[0:1], v2, off offset:768
	v_cvt_pk_bf16_f32 v2, v12, s0
	global_store_short v[0:1], v2, off offset:2048
	v_cvt_pk_bf16_f32 v2, v13, s0
	global_store_short v[0:1], v2, off offset:2304
	v_cvt_pk_bf16_f32 v2, v14, s0
	global_store_short v[0:1], v2, off offset:2560
	v_cvt_pk_bf16_f32 v2, v15, s0
	global_store_short v[0:1], v2, off offset:2816
	v_add_f32_e32 v0, v33, v49
	ds_bpermute_b32 v1, v48, v0
	s_and_saveexec_b64 s[2:3], vcc
	s_cbranch_execz .LBB0_625
	s_lshl_b64 s[4:5], s[18:19], 9
	v_readlane_b32 s6, v254, 61
	v_readlane_b32 s7, v254, 62
	s_add_u32 s4, s6, s4
	s_waitcnt lgkmcnt(0)
	v_add_f32_e32 v0, v0, v1
	s_addc_u32 s5, s7, s5
	v_lshlrev_b32_e32 v1, 2, v47
	global_store_dword v1, v0, s[4:5]
